# counted LDS waits: every lgkmcnt(0) inside the three attention tile loops replaced by the minimal counted wait at the first consumer
# baseline (speedup 1.0000x reference)
.LBB0_2781:
	s_add_i32 s46, s15, 1
	s_cmp_lt_u32 s15, 3
	s_cselect_b32 s48, s46, s15
	s_cselect_b32 s49, s38, s39
	s_lshl_b32 s48, s48, 6
	s_add_i32 s48, s48, s49
	s_ashr_i32 s49, s48, 31
	s_lshl_b64 s[50:51], s[48:49], 1
	s_add_u32 s50, s12, s50
	v_mad_i64_i32 v[2:3], s[48:49], s48, v242, v[132:133]
	s_addc_u32 s51, s13, s51
	s_add_i32 s48, s14, s6
	s_mov_b32 m0, s48
	s_nop 0
	global_load_lds_dwordx4 v[2:3], off
	s_add_i32 m0, s48, 0x2000
	v_lshl_add_u64 v[2:3], v[128:129], 1, s[50:51]
	global_load_lds_dwordx4 v[2:3], off
	v_lshl_add_u64 v[2:3], v[130:131], 1, s[50:51]
	s_add_i32 m0, s48, 0x4000
	s_mov_b32 s48, s7
	global_load_lds_dwordx4 v[2:3], off
	v_add_u32_e32 v0, s48, v137
	ds_read_b128 v[2:5], v0 offset:8192
	ds_read_b128 v[6:9], v0 offset:12288
	ds_read_b128 v[10:13], v0 offset:16384
	ds_read_b128 v[140:143], v0 offset:20480
	s_mov_b32 s7, s47
	v_exp_f32_e32 v14, v96
	v_exp_f32_e32 v144, v97
	v_exp_f32_e32 v98, v98
	v_exp_f32_e32 v146, v99
	v_exp_f32_e32 v15, v100
	v_exp_f32_e32 v145, v101
	v_exp_f32_e32 v99, v102
	v_exp_f32_e32 v147, v103
	v_add_u32_e32 v0, s48, v136
	v_pk_add_f32 v[96:97], v[14:15], v[144:145]
	v_pk_add_f32 v[100:101], v[98:99], v[146:147]
	s_nop 0
	v_pk_add_f32 v[96:97], v[96:97], v[100:101]
	v_cvt_pk_bf16_f32 v99, v99, v147
	v_pk_add_f32 v[156:157], v[96:97], v[96:97] op_sel_hi:[0,1]
	v_cvt_pk_bf16_f32 v96, v14, v144
	v_cvt_pk_bf16_f32 v97, v98, v146
	v_cvt_pk_bf16_f32 v98, v15, v145
	ds_read_b128 v[100:103], v0 offset:8192
	ds_read_b128 v[144:147], v0 offset:12288
	ds_read_b128 v[148:151], v0 offset:16384
	ds_read_b128 v[152:155], v0 offset:20480
	s_waitcnt lgkmcnt(7)
	v_mfma_f32_32x32x16_bf16 v[64:79], v[2:5], v[96:99], v[64:79]
	s_waitcnt lgkmcnt(6)
	v_mfma_f32_32x32x16_bf16 v[48:63], v[6:9], v[96:99], v[48:63]
	s_waitcnt lgkmcnt(5)
	v_mfma_f32_32x32x16_bf16 v[32:47], v[10:13], v[96:99], v[32:47]
	s_waitcnt lgkmcnt(4)
	v_mfma_f32_32x32x16_bf16 v[16:31], v[140:143], v[96:99], v[16:31]
	v_exp_f32_e32 v2, v104
	v_exp_f32_e32 v4, v105
	v_exp_f32_e32 v3, v106
	v_exp_f32_e32 v5, v107
	v_exp_f32_e32 v6, v108
	v_exp_f32_e32 v8, v109
	v_exp_f32_e32 v7, v110
	v_exp_f32_e32 v9, v111
	v_pk_add_f32 v[10:11], v[2:3], v[4:5]
	v_add_u32_e32 v0, s48, v135
	v_pk_add_f32 v[14:15], v[10:11], v[10:11] op_sel_hi:[0,1]
	v_pk_add_f32 v[10:11], v[6:7], v[8:9]
	v_cvt_pk_bf16_f32 v2, v2, v4
	v_pk_add_f32 v[140:141], v[10:11], v[10:11] op_sel_hi:[0,1]
	v_cvt_pk_bf16_f32 v3, v3, v5
	v_cvt_pk_bf16_f32 v4, v6, v8
	v_cvt_pk_bf16_f32 v5, v7, v9
	ds_read_b128 v[6:9], v0 offset:8192
	ds_read_b128 v[10:13], v0 offset:12288
	ds_read_b128 v[96:99], v0 offset:16384
	ds_read_b128 v[104:107], v0 offset:20480
	s_waitcnt lgkmcnt(7)
	v_mfma_f32_32x32x16_bf16 v[64:79], v[100:103], v[2:5], v[64:79]
	s_waitcnt lgkmcnt(6)
	v_mfma_f32_32x32x16_bf16 v[48:63], v[144:147], v[2:5], v[48:63]
	s_waitcnt lgkmcnt(5)
	v_mfma_f32_32x32x16_bf16 v[32:47], v[148:151], v[2:5], v[32:47]
	s_waitcnt lgkmcnt(4)
	v_mfma_f32_32x32x16_bf16 v[16:31], v[152:155], v[2:5], v[16:31]
	v_exp_f32_e32 v0, v80
	v_exp_f32_e32 v2, v81
	v_exp_f32_e32 v3, v82
	v_exp_f32_e32 v4, v83
	v_exp_f32_e32 v5, v84
	v_exp_f32_e32 v14, v85
	v_exp_f32_e32 v80, v86
	v_exp_f32_e32 v81, v87
	v_add_f32_e32 v143, v0, v2
	v_cvt_pk_bf16_f32 v2, v0, v2
	v_add_u32_e32 v0, s48, v134
	v_add_f32_e32 v145, v3, v4
	v_add_f32_e32 v147, v5, v14
	v_add_f32_e32 v149, v80, v81
	v_cvt_pk_bf16_f32 v3, v3, v4
	v_cvt_pk_bf16_f32 v4, v5, v14
	v_cvt_pk_bf16_f32 v5, v80, v81
	ds_read_b128 v[80:83], v0 offset:8192
	ds_read_b128 v[84:87], v0 offset:12288
	ds_read_b128 v[100:103], v0 offset:16384
	ds_read_b128 v[108:111], v0 offset:20480
	s_waitcnt lgkmcnt(7)
	v_mfma_f32_32x32x16_bf16 v[64:79], v[6:9], v[2:5], v[64:79]
	s_waitcnt lgkmcnt(6)
	v_mfma_f32_32x32x16_bf16 v[48:63], v[10:13], v[2:5], v[48:63]
	s_waitcnt lgkmcnt(5)
	v_mfma_f32_32x32x16_bf16 v[32:47], v[96:99], v[2:5], v[32:47]
	s_waitcnt lgkmcnt(4)
	v_mfma_f32_32x32x16_bf16 v[16:31], v[104:107], v[2:5], v[16:31]
	v_exp_f32_e32 v142, v88
	v_exp_f32_e32 v144, v89
	v_exp_f32_e32 v146, v90
	v_exp_f32_e32 v148, v91
	v_exp_f32_e32 v14, v92
	v_exp_f32_e32 v140, v93
	v_exp_f32_e32 v156, v94
	v_exp_f32_e32 v0, v95
	v_cvt_pk_bf16_f32 v2, v142, v144
	v_cvt_pk_bf16_f32 v3, v146, v148
	v_cvt_pk_bf16_f32 v4, v14, v140
	v_cvt_pk_bf16_f32 v5, v156, v0
	s_nop 1
	s_waitcnt lgkmcnt(3)
	v_mfma_f32_32x32x16_bf16 v[64:79], v[80:83], v[2:5], v[64:79]
	v_add_f32_e64 v6, v142, v144
	v_add_f32_e64 v7, v143, v145
	v_add_f32_e64 v8, v146, v148
	v_add_f32_e64 v9, v147, v149
	v_add_f32_e64 v10, v156, v0
	v_add_f32_e64 v11, v157, v1
	v_pk_add_f32 v[6:7], v[6:7], v[8:9]
	v_pk_add_f32 v[8:9], v[14:15], v[140:141]
	s_nop 0
	v_pk_add_f32 v[8:9], v[8:9], v[10:11]
	s_waitcnt lgkmcnt(2)
	v_mfma_f32_32x32x16_bf16 v[48:63], v[84:87], v[2:5], v[48:63]
	v_add_f32_e64 v6, v6, v8
	v_add_f32_e64 v7, v7, v9
	v_pk_add_f32 v[6:7], v[6:7], v[6:7] op_sel:[0,1] op_sel_hi:[1,0]
	s_waitcnt lgkmcnt(1)
	v_mfma_f32_32x32x16_bf16 v[32:47], v[100:103], v[2:5], v[32:47]
	s_waitcnt lgkmcnt(0)
	v_mfma_f32_32x32x16_bf16 v[16:31], v[108:111], v[2:5], v[16:31]
	v_mov_b32_e32 v0, v6
	s_nop 1
	v_permlane32_swap_b32_e32 v6, v0
	v_add_f32_e32 v0, v6, v0
	v_add_f32_e32 v139, v139, v0
	v_add_u32_e32 v0, s7, v137
	ds_read_b128 v[2:5], v0
	ds_read_b128 v[6:9], v0 offset:4096
	v_add_u32_e32 v0, s7, v136
	ds_read_b128 v[10:13], v0
	ds_read_b128 v[140:143], v0 offset:4096
	v_add_u32_e32 v0, s7, v135
	v_add_u32_e32 v14, s7, v134
	ds_read_b128 v[144:147], v0
	ds_read_b128 v[148:151], v0 offset:4096
	ds_read_b128 v[152:155], v14
	ds_read_b128 v[156:159], v14 offset:4096
	v_xor_b32_e32 v80, 0x80000000, v138
	v_mov_b32_e32 v81, v80
	v_mov_b32_e32 v82, v80
	v_mov_b32_e32 v83, v80
	v_mov_b32_e32 v84, v80
	v_mov_b32_e32 v85, v80
	v_mov_b32_e32 v86, v80
	v_mov_b32_e32 v87, v80
	v_mov_b32_e32 v88, v80
	v_mov_b32_e32 v89, v80
	v_mov_b32_e32 v90, v80
	v_mov_b32_e32 v91, v80
	v_mov_b32_e32 v92, v80
	v_mov_b32_e32 v93, v80
	v_mov_b32_e32 v94, v80
	v_mov_b32_e32 v95, v80
	s_nop 0
	s_waitcnt lgkmcnt(7)
	v_mfma_f32_32x32x16_bf16 v[96:111], v[2:5], v[124:127], v[80:95]
	s_waitcnt lgkmcnt(5)
	v_mfma_f32_32x32x16_bf16 v[96:111], v[10:13], v[120:123], v[96:111]
	s_waitcnt lgkmcnt(3)
	v_mfma_f32_32x32x16_bf16 v[96:111], v[144:147], v[116:119], v[96:111]
	s_waitcnt lgkmcnt(1)
	v_mfma_f32_32x32x16_bf16 v[96:111], v[152:155], v[112:115], v[96:111]
	v_mfma_f32_32x32x16_bf16 v[80:95], v[6:9], v[124:127], v[80:95]
	s_nop 10
	v_max_f32_e32 v0, v97, v97
	v_max_f32_e32 v2, v96, v96
	v_max_f32_e32 v0, v2, v0
	v_max3_f32 v0, v0, v98, v99
	v_max3_f32 v0, v0, v100, v101
	v_max3_f32 v0, v0, v102, v103
	v_max3_f32 v0, v0, v104, v105
	v_mfma_f32_32x32x16_bf16 v[80:95], v[140:143], v[120:123], v[80:95]
	v_max3_f32 v0, v0, v106, v107
	v_max3_f32 v0, v0, v108, v109
	v_max3_f32 v0, v0, v110, v111
	s_mov_b32 s47, 0x41000000
	v_mfma_f32_32x32x16_bf16 v[80:95], v[148:151], v[116:119], v[80:95]
	s_waitcnt lgkmcnt(0)
	v_mfma_f32_32x32x16_bf16 v[80:95], v[156:159], v[112:115], v[80:95]
	s_nop 11
	v_max3_f32 v0, v0, v80, v81
	v_max3_f32 v0, v0, v82, v83
	v_max3_f32 v0, v0, v84, v85
	v_max3_f32 v0, v0, v86, v87
	v_max3_f32 v0, v0, v88, v89
	v_max3_f32 v0, v0, v90, v91
	v_max3_f32 v0, v0, v92, v93
	v_max3_f32 v0, v0, v94, v95
	v_mov_b32_e32 v2, v0
	s_nop 1
	v_permlane32_swap_b32_e32 v0, v2
	v_max_f32_e32 v2, v2, v2
	v_max_f32_e32 v0, v0, v0
	v_max_f32_e32 v0, v0, v2
	v_cmp_ge_f32_e32 vcc, s47, v0
	s_cmp_eq_u64 vcc, exec
	s_cbranch_scc1 .LBB0_2783
	v_max_f32_e32 v0, v0, v0
	v_max_f32_e32 v2, 0, v0
	v_exp_f32_e64 v0, -v2
	v_add_f32_e32 v138, v138, v2
	v_sub_f32_e32 v111, v111, v2
	v_sub_f32_e32 v110, v110, v2
	v_pk_mul_f32 v[78:79], v[78:79], v[0:1] op_sel_hi:[1,0]
	v_pk_mul_f32 v[76:77], v[76:77], v[0:1] op_sel_hi:[1,0]
	v_pk_mul_f32 v[74:75], v[74:75], v[0:1] op_sel_hi:[1,0]
	v_pk_mul_f32 v[72:73], v[72:73], v[0:1] op_sel_hi:[1,0]
	v_pk_mul_f32 v[70:71], v[70:71], v[0:1] op_sel_hi:[1,0]
	v_pk_mul_f32 v[68:69], v[68:69], v[0:1] op_sel_hi:[1,0]
	v_pk_mul_f32 v[66:67], v[66:67], v[0:1] op_sel_hi:[1,0]
	v_pk_mul_f32 v[64:65], v[64:65], v[0:1] op_sel_hi:[1,0]
	v_pk_mul_f32 v[62:63], v[62:63], v[0:1] op_sel_hi:[1,0]
	v_pk_mul_f32 v[60:61], v[60:61], v[0:1] op_sel_hi:[1,0]
	v_pk_mul_f32 v[58:59], v[58:59], v[0:1] op_sel_hi:[1,0]
	v_pk_mul_f32 v[56:57], v[56:57], v[0:1] op_sel_hi:[1,0]
	v_pk_mul_f32 v[54:55], v[54:55], v[0:1] op_sel_hi:[1,0]
	v_pk_mul_f32 v[52:53], v[52:53], v[0:1] op_sel_hi:[1,0]
	v_pk_mul_f32 v[50:51], v[50:51], v[0:1] op_sel_hi:[1,0]
	v_pk_mul_f32 v[48:49], v[48:49], v[0:1] op_sel_hi:[1,0]
	v_pk_mul_f32 v[46:47], v[46:47], v[0:1] op_sel_hi:[1,0]
	v_pk_mul_f32 v[44:45], v[44:45], v[0:1] op_sel_hi:[1,0]
	v_pk_mul_f32 v[42:43], v[42:43], v[0:1] op_sel_hi:[1,0]
	v_pk_mul_f32 v[40:41], v[40:41], v[0:1] op_sel_hi:[1,0]
	v_pk_mul_f32 v[38:39], v[38:39], v[0:1] op_sel_hi:[1,0]
	v_pk_mul_f32 v[36:37], v[36:37], v[0:1] op_sel_hi:[1,0]
	v_pk_mul_f32 v[34:35], v[34:35], v[0:1] op_sel_hi:[1,0]
	v_pk_mul_f32 v[32:33], v[32:33], v[0:1] op_sel_hi:[1,0]
	v_pk_mul_f32 v[30:31], v[30:31], v[0:1] op_sel_hi:[1,0]
	v_pk_mul_f32 v[28:29], v[28:29], v[0:1] op_sel_hi:[1,0]
	v_pk_mul_f32 v[26:27], v[26:27], v[0:1] op_sel_hi:[1,0]
	v_pk_mul_f32 v[24:25], v[24:25], v[0:1] op_sel_hi:[1,0]
	v_pk_mul_f32 v[22:23], v[22:23], v[0:1] op_sel_hi:[1,0]
	v_pk_mul_f32 v[20:21], v[20:21], v[0:1] op_sel_hi:[1,0]
	v_pk_mul_f32 v[18:19], v[18:19], v[0:1] op_sel_hi:[1,0]
	v_pk_mul_f32 v[16:17], v[16:17], v[0:1] op_sel_hi:[1,0]
	v_sub_f32_e32 v109, v109, v2
	v_sub_f32_e32 v108, v108, v2
	v_sub_f32_e32 v107, v107, v2
	v_sub_f32_e32 v106, v106, v2
	v_sub_f32_e32 v105, v105, v2
	v_sub_f32_e32 v104, v104, v2
	v_sub_f32_e32 v103, v103, v2
	v_sub_f32_e32 v102, v102, v2
	v_sub_f32_e32 v101, v101, v2
	v_sub_f32_e32 v100, v100, v2
	v_sub_f32_e32 v99, v99, v2
	v_sub_f32_e32 v98, v98, v2
	v_sub_f32_e32 v97, v97, v2
	v_sub_f32_e32 v96, v96, v2
	v_sub_f32_e32 v95, v95, v2
	v_sub_f32_e32 v94, v94, v2
	v_sub_f32_e32 v93, v93, v2
	v_sub_f32_e32 v92, v92, v2
	v_sub_f32_e32 v91, v91, v2
	v_sub_f32_e32 v90, v90, v2
	v_sub_f32_e32 v89, v89, v2
	v_sub_f32_e32 v88, v88, v2
	v_sub_f32_e32 v87, v87, v2
	v_sub_f32_e32 v86, v86, v2
	v_sub_f32_e32 v85, v85, v2
	v_sub_f32_e32 v84, v84, v2
	v_sub_f32_e32 v83, v83, v2
	v_sub_f32_e32 v82, v82, v2
	v_sub_f32_e32 v81, v81, v2
	v_sub_f32_e32 v80, v80, v2
	v_mul_f32_e32 v139, v139, v0

; #define A2_SETVC(SOFF) _Pragma("unroll") for (int _i = 0; _i < 4; ++_i) vc[_i] = vbase[_i] + (unsigned)(SOFF)
; template <int TYPE>
; __device__ __forceinline__ void attn_mfma_unit2(const AttnCtx& A, unsigned char* ws, LAS unsigned char* lds, int tid, const AUnit& u) {
;     ...
;             if (actP) { A2_SETVC(sprv); A2_FSM_PV(sA0, sA1, 0); }
.LBB0_2816:
	s_andn2_b64 vcc, exec, s[8:9]
	s_cbranch_vccnz .LBB0_2818
	v_add_u32_e32 v0, s12, v198
	ds_read_b128 v[2:5], v0 offset:16384
	ds_read_b128 v[6:9], v0 offset:20480
	ds_read_b128 v[10:13], v0 offset:24576
	ds_read_b128 v[116:119], v0 offset:28672
	v_exp_f32_e32 v14, v96
	v_exp_f32_e32 v112, v97
	v_exp_f32_e32 v132, v98
	v_exp_f32_e32 v114, v99
	v_exp_f32_e32 v15, v100
	v_exp_f32_e32 v113, v101
	v_exp_f32_e32 v133, v102
	v_exp_f32_e32 v115, v103
	v_add_u32_e32 v0, s12, v199
	v_pk_add_f32 v[96:97], v[14:15], v[112:113]
	v_cvt_pk_bf16_f32 v120, v14, v112
	v_pk_add_f32 v[98:99], v[132:133], v[114:115]
	v_cvt_pk_bf16_f32 v121, v132, v114
	v_pk_add_f32 v[96:97], v[96:97], v[98:99]
	v_cvt_pk_bf16_f32 v122, v15, v113
	v_pk_add_f32 v[136:137], v[96:97], v[96:97] op_sel_hi:[0,1]
	ds_read_b128 v[96:99], v0 offset:16384
	ds_read_b128 v[100:103], v0 offset:20480
	ds_read_b128 v[124:127], v0 offset:24576
	ds_read_b128 v[128:131], v0 offset:28672
	v_cvt_pk_bf16_f32 v123, v133, v115
	s_nop 0
	s_waitcnt lgkmcnt(7)
	v_mfma_f32_32x32x16_bf16 v[64:79], v[2:5], v[120:123], v[64:79]
	s_waitcnt lgkmcnt(6)
	v_mfma_f32_32x32x16_bf16 v[48:63], v[6:9], v[120:123], v[48:63]
	s_waitcnt lgkmcnt(5)
	v_mfma_f32_32x32x16_bf16 v[32:47], v[10:13], v[120:123], v[32:47]
	s_waitcnt lgkmcnt(4)
	v_mfma_f32_32x32x16_bf16 v[16:31], v[116:119], v[120:123], v[16:31]
	v_exp_f32_e32 v116, v104
	v_exp_f32_e32 v117, v105
	v_exp_f32_e32 v118, v106
	v_exp_f32_e32 v119, v107
	v_exp_f32_e32 v120, v108
	v_exp_f32_e32 v121, v109
	v_exp_f32_e32 v122, v110
	v_exp_f32_e32 v123, v111
	v_mov_b32_e32 v2, v116
	v_mov_b32_e32 v3, v118
	v_mov_b32_e32 v4, v117
	v_mov_b32_e32 v5, v119
	v_pk_add_f32 v[2:3], v[2:3], v[4:5]
	v_mov_b32_e32 v108, v14
	v_mov_b32_e32 v109, v112
	v_mov_b32_e32 v112, v15
	v_pk_add_f32 v[14:15], v[2:3], v[2:3] op_sel_hi:[0,1]
	v_mov_b32_e32 v2, v120
	v_mov_b32_e32 v3, v122
	v_mov_b32_e32 v4, v121
	v_mov_b32_e32 v5, v123
	v_pk_add_f32 v[2:3], v[2:3], v[4:5]
	v_add_u32_e32 v0, s12, v200
	v_pk_add_f32 v[138:139], v[2:3], v[2:3] op_sel_hi:[0,1]
	ds_read_b128 v[2:5], v0 offset:16384
	ds_read_b128 v[6:9], v0 offset:20480
	ds_read_b128 v[10:13], v0 offset:24576
	ds_read_b128 v[104:107], v0 offset:28672
	v_mov_b32_e32 v110, v132
	v_mov_b32_e32 v111, v114
	v_mov_b32_e32 v114, v133
	v_cvt_pk_bf16_f32 v132, v116, v117
	v_cvt_pk_bf16_f32 v133, v118, v119
	v_cvt_pk_bf16_f32 v134, v120, v121
	v_cvt_pk_bf16_f32 v135, v122, v123
	s_nop 1
	s_waitcnt lgkmcnt(7)
	v_mfma_f32_32x32x16_bf16 v[64:79], v[96:99], v[132:135], v[64:79]
	s_waitcnt lgkmcnt(6)
	v_mfma_f32_32x32x16_bf16 v[48:63], v[100:103], v[132:135], v[48:63]
	s_waitcnt lgkmcnt(5)
	v_mfma_f32_32x32x16_bf16 v[32:47], v[124:127], v[132:135], v[32:47]
	s_waitcnt lgkmcnt(4)
	v_mfma_f32_32x32x16_bf16 v[16:31], v[128:131], v[132:135], v[16:31]
	v_add_u32_e32 v0, s12, v201
	ds_read_b128 v[96:99], v0 offset:16384
	ds_read_b128 v[100:103], v0 offset:20480
	ds_read_b128 v[124:127], v0 offset:24576
	ds_read_b128 v[128:131], v0 offset:28672
	v_exp_f32_e32 v80, v80
	v_exp_f32_e32 v81, v81
	v_exp_f32_e32 v82, v82
	v_exp_f32_e32 v83, v83
	v_exp_f32_e32 v84, v84
	v_exp_f32_e32 v85, v85
	v_exp_f32_e32 v86, v86
	v_exp_f32_e32 v87, v87
	v_add_f32_e32 v141, v80, v81
	v_add_f32_e32 v143, v82, v83
	v_add_f32_e32 v213, v84, v85
	v_add_f32_e32 v215, v86, v87
	v_cvt_pk_bf16_f32 v132, v80, v81
	v_cvt_pk_bf16_f32 v133, v82, v83
	v_cvt_pk_bf16_f32 v134, v84, v85
	v_cvt_pk_bf16_f32 v135, v86, v87
	s_nop 0
	s_waitcnt lgkmcnt(7)
	v_mfma_f32_32x32x16_bf16 v[64:79], v[2:5], v[132:135], v[64:79]
	s_waitcnt lgkmcnt(6)
	v_mfma_f32_32x32x16_bf16 v[48:63], v[6:9], v[132:135], v[48:63]
	s_waitcnt lgkmcnt(5)
	v_mfma_f32_32x32x16_bf16 v[32:47], v[10:13], v[132:135], v[32:47]
	s_waitcnt lgkmcnt(4)
	v_mfma_f32_32x32x16_bf16 v[16:31], v[104:107], v[132:135], v[16:31]
	v_exp_f32_e32 v88, v88
	v_exp_f32_e32 v89, v89
	v_exp_f32_e32 v90, v90
	v_exp_f32_e32 v91, v91
	v_exp_f32_e32 v92, v92
	v_exp_f32_e32 v93, v93
	v_exp_f32_e32 v94, v94
	v_exp_f32_e32 v95, v95
	v_cvt_pk_bf16_f32 v2, v88, v89
	v_cvt_pk_bf16_f32 v3, v90, v91
	v_cvt_pk_bf16_f32 v4, v92, v93
	v_cvt_pk_bf16_f32 v5, v94, v95
	s_nop 1
	s_waitcnt lgkmcnt(3)
	v_mfma_f32_32x32x16_bf16 v[64:79], v[96:99], v[2:5], v[64:79]
	v_mov_b32_e32 v140, v88
	v_mov_b32_e32 v142, v89
	v_mov_b32_e32 v212, v90
	v_mov_b32_e32 v214, v91
	v_add_f32_e64 v6, v140, v142
	v_add_f32_e64 v7, v141, v143
	v_pk_add_f32 v[8:9], v[212:213], v[214:215]
	v_mov_b32_e32 v14, v92
	s_waitcnt lgkmcnt(2)
	v_mfma_f32_32x32x16_bf16 v[48:63], v[100:103], v[2:5], v[48:63]
	v_mov_b32_e32 v138, v93
	v_mov_b32_e32 v136, v94
	v_mov_b32_e32 v0, v95
	v_add_f32_e64 v6, v6, v8
	v_add_f32_e64 v7, v7, v9
	v_pk_add_f32 v[8:9], v[14:15], v[138:139]
	v_pk_add_f32 v[10:11], v[136:137], v[0:1]
	s_waitcnt lgkmcnt(1)
	v_mfma_f32_32x32x16_bf16 v[32:47], v[124:127], v[2:5], v[32:47]
	v_add_f32_e64 v8, v8, v10
	v_add_f32_e64 v9, v9, v11
	v_add_f32_e64 v6, v6, v8
	v_add_f32_e64 v7, v7, v9
	v_pk_add_f32 v[6:7], v[6:7], v[6:7] op_sel:[0,1] op_sel_hi:[1,0]
	s_waitcnt lgkmcnt(0)
	v_mfma_f32_32x32x16_bf16 v[16:31], v[128:131], v[2:5], v[16:31]
	v_mov_b32_e32 v0, v6
	s_nop 1
	v_permlane32_swap_b32_e32 v6, v0
	v_add_f32_e32 v0, v6, v0
	v_mov_b64_e32 v[96:97], v[108:109]
	v_add_f32_e32 v190, v190, v0
	v_mov_b64_e32 v[98:99], v[110:111]
	v_mov_b64_e32 v[100:101], v[112:113]
	v_mov_b64_e32 v[102:103], v[114:115]
	v_mov_b64_e32 v[104:105], v[116:117]
	v_mov_b64_e32 v[106:107], v[118:119]
	v_mov_b64_e32 v[108:109], v[120:121]
	v_mov_b64_e32 v[110:111], v[122:123]

.LBB0_2904:
	v_add_u32_e32 v0, s28, v183
	ds_read_b128 v[2:5], v0 offset:24576
	ds_read_b128 v[6:9], v0 offset:28672
	ds_read_b128 v[10:13], v0 offset:32768
	ds_read_b128 v[184:187], v0 offset:36864
	v_exp_f32_e32 v14, v96
	v_exp_f32_e32 v190, v97
	v_exp_f32_e32 v98, v98
	v_exp_f32_e32 v192, v99
	v_exp_f32_e32 v15, v100
	v_exp_f32_e32 v191, v101
	v_exp_f32_e32 v99, v102
	v_exp_f32_e32 v193, v103
	v_add_u32_e32 v0, s28, v182
	v_pk_add_f32 v[96:97], v[14:15], v[190:191]
	v_pk_add_f32 v[100:101], v[98:99], v[192:193]
	s_nop 0
	v_pk_add_f32 v[96:97], v[96:97], v[100:101]
	v_cvt_pk_bf16_f32 v99, v99, v193
	v_pk_add_f32 v[202:203], v[96:97], v[96:97] op_sel_hi:[0,1]
	v_cvt_pk_bf16_f32 v96, v14, v190
	v_cvt_pk_bf16_f32 v97, v98, v192
	v_cvt_pk_bf16_f32 v98, v15, v191
	ds_read_b128 v[100:103], v0 offset:24576
	ds_read_b128 v[190:193], v0 offset:28672
	ds_read_b128 v[194:197], v0 offset:32768
	ds_read_b128 v[198:201], v0 offset:36864
	s_waitcnt lgkmcnt(7)
	v_mfma_f32_32x32x16_bf16 v[64:79], v[2:5], v[96:99], v[64:79]
	s_waitcnt lgkmcnt(6)
	v_mfma_f32_32x32x16_bf16 v[48:63], v[6:9], v[96:99], v[48:63]
	s_waitcnt lgkmcnt(5)
	v_mfma_f32_32x32x16_bf16 v[32:47], v[10:13], v[96:99], v[32:47]
	s_waitcnt lgkmcnt(4)
	v_mfma_f32_32x32x16_bf16 v[16:31], v[184:187], v[96:99], v[16:31]
	v_exp_f32_e32 v2, v104
	v_exp_f32_e32 v4, v105
	v_exp_f32_e32 v3, v106
	v_exp_f32_e32 v5, v107
	v_exp_f32_e32 v6, v108
	v_exp_f32_e32 v8, v109
	v_exp_f32_e32 v7, v110
	v_exp_f32_e32 v9, v111
	v_pk_add_f32 v[10:11], v[2:3], v[4:5]
	v_add_u32_e32 v0, s28, v180
	v_pk_add_f32 v[14:15], v[10:11], v[10:11] op_sel_hi:[0,1]
	v_pk_add_f32 v[10:11], v[6:7], v[8:9]
	v_cvt_pk_bf16_f32 v2, v2, v4
	v_pk_add_f32 v[184:185], v[10:11], v[10:11] op_sel_hi:[0,1]
	v_cvt_pk_bf16_f32 v3, v3, v5
	v_cvt_pk_bf16_f32 v4, v6, v8
	v_cvt_pk_bf16_f32 v5, v7, v9
	ds_read_b128 v[6:9], v0 offset:24576
	ds_read_b128 v[10:13], v0 offset:28672
	ds_read_b128 v[96:99], v0 offset:32768
	ds_read_b128 v[104:107], v0 offset:36864
	s_waitcnt lgkmcnt(7)
	v_mfma_f32_32x32x16_bf16 v[64:79], v[100:103], v[2:5], v[64:79]
	s_waitcnt lgkmcnt(6)
	v_mfma_f32_32x32x16_bf16 v[48:63], v[190:193], v[2:5], v[48:63]
	s_waitcnt lgkmcnt(5)
	v_mfma_f32_32x32x16_bf16 v[32:47], v[194:197], v[2:5], v[32:47]
	s_waitcnt lgkmcnt(4)
	v_mfma_f32_32x32x16_bf16 v[16:31], v[198:201], v[2:5], v[16:31]
	v_exp_f32_e32 v0, v80
	v_exp_f32_e32 v2, v81
	v_exp_f32_e32 v3, v82
	v_exp_f32_e32 v4, v83
	v_exp_f32_e32 v5, v84
	v_exp_f32_e32 v14, v85
	v_exp_f32_e32 v80, v86
	v_exp_f32_e32 v81, v87
	v_add_f32_e32 v187, v0, v2
	v_cvt_pk_bf16_f32 v2, v0, v2
	v_add_u32_e32 v0, s28, v175
	v_add_f32_e32 v191, v3, v4
	v_add_f32_e32 v193, v5, v14
	v_add_f32_e32 v195, v80, v81
	v_cvt_pk_bf16_f32 v3, v3, v4
	v_cvt_pk_bf16_f32 v4, v5, v14
	v_cvt_pk_bf16_f32 v5, v80, v81
	ds_read_b128 v[80:83], v0 offset:24576
	ds_read_b128 v[84:87], v0 offset:28672
	ds_read_b128 v[100:103], v0 offset:32768
	ds_read_b128 v[108:111], v0 offset:36864
	s_waitcnt lgkmcnt(7)
	v_mfma_f32_32x32x16_bf16 v[64:79], v[6:9], v[2:5], v[64:79]
	s_waitcnt lgkmcnt(6)
	v_mfma_f32_32x32x16_bf16 v[48:63], v[10:13], v[2:5], v[48:63]
	s_waitcnt lgkmcnt(5)
	v_mfma_f32_32x32x16_bf16 v[32:47], v[96:99], v[2:5], v[32:47]
	s_waitcnt lgkmcnt(4)
	v_mfma_f32_32x32x16_bf16 v[16:31], v[104:107], v[2:5], v[16:31]
	v_exp_f32_e32 v186, v88
	v_exp_f32_e32 v190, v89
	v_exp_f32_e32 v192, v90
	v_exp_f32_e32 v194, v91
	v_exp_f32_e32 v14, v92
	v_exp_f32_e32 v184, v93
	v_exp_f32_e32 v202, v94
	v_exp_f32_e32 v0, v95
	v_cvt_pk_bf16_f32 v2, v186, v190
	v_cvt_pk_bf16_f32 v3, v192, v194
	v_cvt_pk_bf16_f32 v4, v14, v184
	v_cvt_pk_bf16_f32 v5, v202, v0
	s_nop 1
	s_waitcnt lgkmcnt(3)
	v_mfma_f32_32x32x16_bf16 v[64:79], v[80:83], v[2:5], v[64:79]
	v_add_f32_e64 v6, v186, v190
	v_add_f32_e64 v7, v187, v191
	v_add_f32_e64 v8, v192, v194
	v_add_f32_e64 v9, v193, v195
	v_add_f32_e64 v10, v202, v0
	v_add_f32_e64 v11, v203, v1
	v_pk_add_f32 v[6:7], v[6:7], v[8:9]
	v_pk_add_f32 v[8:9], v[14:15], v[184:185]
	s_nop 0
	v_pk_add_f32 v[8:9], v[8:9], v[10:11]
	s_waitcnt lgkmcnt(2)
	v_mfma_f32_32x32x16_bf16 v[48:63], v[84:87], v[2:5], v[48:63]
	v_add_f32_e64 v6, v6, v8
	v_add_f32_e64 v7, v7, v9
	v_pk_add_f32 v[6:7], v[6:7], v[6:7] op_sel:[0,1] op_sel_hi:[1,0]
	s_waitcnt lgkmcnt(1)
	v_mfma_f32_32x32x16_bf16 v[32:47], v[100:103], v[2:5], v[32:47]
	s_waitcnt lgkmcnt(0)
	v_mfma_f32_32x32x16_bf16 v[16:31], v[108:111], v[2:5], v[16:31]
	v_mov_b32_e32 v0, v6
	s_nop 1
	v_permlane32_swap_b32_e32 v6, v0
	v_add_f32_e32 v0, v6, v0
	v_add_f32_e32 v171, v171, v0
	v_add_u32_e32 v0, s1, v174
	v_add_u32_e32 v14, s1, v173
	v_add_u32_e32 v15, s1, v170
	ds_read_b128 v[2:5], v0
	ds_read_b128 v[6:9], v0 offset:12288
	ds_read_b128 v[10:13], v14
	ds_read_b128 v[184:187], v14 offset:12288
	v_add_u32_e32 v206, s1, v172
	ds_read_b128 v[190:193], v15
	ds_read_b128 v[194:197], v15 offset:12288
	ds_read_b128 v[198:201], v206
	ds_read_b128 v[202:205], v206 offset:12288
	v_xor_b32_e32 v80, 0x80000000, v181
	v_mov_b32_e32 v81, v80
	v_mov_b32_e32 v82, v80
	v_mov_b32_e32 v83, v80
	v_mov_b32_e32 v84, v80
	v_mov_b32_e32 v85, v80
	v_mov_b32_e32 v86, v80
	v_mov_b32_e32 v87, v80
	v_mov_b32_e32 v88, v80
	v_mov_b32_e32 v89, v80
	v_mov_b32_e32 v90, v80
	v_mov_b32_e32 v91, v80
	v_mov_b32_e32 v92, v80
	v_mov_b32_e32 v93, v80
	v_mov_b32_e32 v94, v80
	v_mov_b32_e32 v95, v80
	s_nop 0
	s_waitcnt lgkmcnt(7)
	v_mfma_f32_32x32x16_bf16 v[96:111], v[2:5], v[112:115], v[80:95]
	s_waitcnt lgkmcnt(6)
	v_mfma_f32_32x32x16_bf16 v[80:95], v[6:9], v[112:115], v[80:95]
	s_waitcnt lgkmcnt(5)
	v_mfma_f32_32x32x16_bf16 v[96:111], v[10:13], v[116:119], v[96:111]
	s_waitcnt lgkmcnt(4)
	v_mfma_f32_32x32x16_bf16 v[80:95], v[184:187], v[116:119], v[80:95]
	ds_read_b128 v[2:5], v14 offset:12416
	ds_read_b128 v[6:9], v14 offset:128
	ds_read_b128 v[10:13], v0 offset:12416
	ds_read_b128 v[184:187], v0 offset:128
	s_waitcnt lgkmcnt(7)
	v_mfma_f32_32x32x16_bf16 v[96:111], v[190:193], v[120:123], v[96:111]
	s_waitcnt lgkmcnt(6)
	v_mfma_f32_32x32x16_bf16 v[80:95], v[194:197], v[120:123], v[80:95]
	s_waitcnt lgkmcnt(5)
	v_mfma_f32_32x32x16_bf16 v[96:111], v[198:201], v[124:127], v[96:111]
	s_waitcnt lgkmcnt(4)
	v_mfma_f32_32x32x16_bf16 v[80:95], v[202:205], v[124:127], v[80:95]
	ds_read_b128 v[190:193], v15 offset:128
	ds_read_b128 v[194:197], v15 offset:12416
	ds_read_b128 v[198:201], v206 offset:128
	ds_read_b128 v[202:205], v206 offset:12416
	s_waitcnt lgkmcnt(4)
	v_mfma_f32_32x32x16_bf16 v[96:111], v[184:187], v[128:131], v[96:111]
	v_mfma_f32_32x32x16_bf16 v[80:95], v[10:13], v[128:131], v[80:95]
	v_mfma_f32_32x32x16_bf16 v[96:111], v[6:9], v[132:135], v[96:111]
	v_mfma_f32_32x32x16_bf16 v[80:95], v[2:5], v[132:135], v[80:95]
	ds_read_b128 v[2:5], v14 offset:12544
	ds_read_b128 v[6:9], v14 offset:256
	ds_read_b128 v[10:13], v0 offset:12544
	ds_read_b128 v[184:187], v0 offset:256
	s_waitcnt lgkmcnt(7)
	v_mfma_f32_32x32x16_bf16 v[96:111], v[190:193], v[136:139], v[96:111]
	s_waitcnt lgkmcnt(6)
	v_mfma_f32_32x32x16_bf16 v[80:95], v[194:197], v[136:139], v[80:95]
	s_waitcnt lgkmcnt(5)
	v_mfma_f32_32x32x16_bf16 v[96:111], v[198:201], v[140:143], v[96:111]
	s_waitcnt lgkmcnt(4)
	v_mfma_f32_32x32x16_bf16 v[80:95], v[202:205], v[140:143], v[80:95]
	ds_read_b128 v[190:193], v15 offset:256
	ds_read_b128 v[194:197], v15 offset:12544
	ds_read_b128 v[198:201], v206 offset:256
	ds_read_b128 v[202:205], v206 offset:12544
	s_waitcnt lgkmcnt(4)
	v_mfma_f32_32x32x16_bf16 v[96:111], v[184:187], v[144:147], v[96:111]
	v_mfma_f32_32x32x16_bf16 v[80:95], v[10:13], v[144:147], v[80:95]
	v_mfma_f32_32x32x16_bf16 v[96:111], v[6:9], v[148:151], v[96:111]
	v_mfma_f32_32x32x16_bf16 v[80:95], v[2:5], v[148:151], v[80:95]
	s_waitcnt lgkmcnt(3)
	v_mfma_f32_32x32x16_bf16 v[96:111], v[190:193], v[152:155], v[96:111]
	s_waitcnt lgkmcnt(1)
	v_mfma_f32_32x32x16_bf16 v[96:111], v[198:201], v[156:159], v[96:111]
	v_mfma_f32_32x32x16_bf16 v[80:95], v[194:197], v[152:155], v[80:95]
	s_nop 10
	v_max_f32_e32 v0, v97, v97
	v_max_f32_e32 v2, v96, v96
	v_max_f32_e32 v0, v2, v0
	v_max3_f32 v0, v0, v98, v99
	v_max3_f32 v0, v0, v100, v101
	v_max3_f32 v0, v0, v102, v103
	v_max3_f32 v0, v0, v104, v105
	s_waitcnt lgkmcnt(0)
	v_mfma_f32_32x32x16_bf16 v[80:95], v[202:205], v[156:159], v[80:95]
	v_max3_f32 v0, v0, v106, v107
	v_max3_f32 v0, v0, v108, v109
	v_max3_f32 v0, v0, v110, v111
	s_mov_b32 s28, 0x41000000
	s_nop 7
	v_max3_f32 v0, v0, v80, v81
	v_max3_f32 v0, v0, v82, v83
	v_max3_f32 v0, v0, v84, v85
	v_max3_f32 v0, v0, v86, v87
	v_max3_f32 v0, v0, v88, v89
	v_max3_f32 v0, v0, v90, v91
	v_max3_f32 v0, v0, v92, v93
	v_max3_f32 v0, v0, v94, v95
	v_mov_b32_e32 v2, v0
	s_nop 1
	v_permlane32_swap_b32_e32 v0, v2
	v_max_f32_e32 v2, v2, v2
	v_max_f32_e32 v0, v0, v0
	v_max_f32_e32 v0, v0, v2
	v_cmp_ge_f32_e32 vcc, s28, v0
	s_cmp_eq_u64 vcc, exec
	s_cbranch_scc1 .LBB0_2906
	v_max_f32_e32 v0, v0, v0
	v_max_f32_e32 v2, 0, v0
	v_exp_f32_e64 v0, -v2
	v_add_f32_e32 v181, v181, v2
	v_sub_f32_e32 v111, v111, v2
	v_sub_f32_e32 v110, v110, v2
	v_pk_mul_f32 v[78:79], v[78:79], v[0:1] op_sel_hi:[1,0]
	v_pk_mul_f32 v[76:77], v[76:77], v[0:1] op_sel_hi:[1,0]
	v_pk_mul_f32 v[74:75], v[74:75], v[0:1] op_sel_hi:[1,0]
	v_pk_mul_f32 v[72:73], v[72:73], v[0:1] op_sel_hi:[1,0]
	v_pk_mul_f32 v[70:71], v[70:71], v[0:1] op_sel_hi:[1,0]
	v_pk_mul_f32 v[68:69], v[68:69], v[0:1] op_sel_hi:[1,0]
	v_pk_mul_f32 v[66:67], v[66:67], v[0:1] op_sel_hi:[1,0]
	v_pk_mul_f32 v[64:65], v[64:65], v[0:1] op_sel_hi:[1,0]
	v_pk_mul_f32 v[62:63], v[62:63], v[0:1] op_sel_hi:[1,0]
	v_pk_mul_f32 v[60:61], v[60:61], v[0:1] op_sel_hi:[1,0]
	v_pk_mul_f32 v[58:59], v[58:59], v[0:1] op_sel_hi:[1,0]
	v_pk_mul_f32 v[56:57], v[56:57], v[0:1] op_sel_hi:[1,0]
	v_pk_mul_f32 v[54:55], v[54:55], v[0:1] op_sel_hi:[1,0]
	v_pk_mul_f32 v[52:53], v[52:53], v[0:1] op_sel_hi:[1,0]
	v_pk_mul_f32 v[50:51], v[50:51], v[0:1] op_sel_hi:[1,0]
	v_pk_mul_f32 v[48:49], v[48:49], v[0:1] op_sel_hi:[1,0]
	v_pk_mul_f32 v[46:47], v[46:47], v[0:1] op_sel_hi:[1,0]
	v_pk_mul_f32 v[44:45], v[44:45], v[0:1] op_sel_hi:[1,0]
	v_pk_mul_f32 v[42:43], v[42:43], v[0:1] op_sel_hi:[1,0]
	v_pk_mul_f32 v[40:41], v[40:41], v[0:1] op_sel_hi:[1,0]
	v_pk_mul_f32 v[38:39], v[38:39], v[0:1] op_sel_hi:[1,0]
	v_pk_mul_f32 v[36:37], v[36:37], v[0:1] op_sel_hi:[1,0]
	v_pk_mul_f32 v[34:35], v[34:35], v[0:1] op_sel_hi:[1,0]
	v_pk_mul_f32 v[32:33], v[32:33], v[0:1] op_sel_hi:[1,0]
	v_pk_mul_f32 v[30:31], v[30:31], v[0:1] op_sel_hi:[1,0]
	v_pk_mul_f32 v[28:29], v[28:29], v[0:1] op_sel_hi:[1,0]
	v_pk_mul_f32 v[26:27], v[26:27], v[0:1] op_sel_hi:[1,0]
	v_pk_mul_f32 v[24:25], v[24:25], v[0:1] op_sel_hi:[1,0]
	v_pk_mul_f32 v[22:23], v[22:23], v[0:1] op_sel_hi:[1,0]
	v_pk_mul_f32 v[20:21], v[20:21], v[0:1] op_sel_hi:[1,0]
	v_pk_mul_f32 v[18:19], v[18:19], v[0:1] op_sel_hi:[1,0]
	v_pk_mul_f32 v[16:17], v[16:17], v[0:1] op_sel_hi:[1,0]
	v_sub_f32_e32 v109, v109, v2
	v_sub_f32_e32 v108, v108, v2
	v_sub_f32_e32 v107, v107, v2
	v_sub_f32_e32 v106, v106, v2
	v_sub_f32_e32 v105, v105, v2
	v_sub_f32_e32 v104, v104, v2
	v_sub_f32_e32 v103, v103, v2
	v_sub_f32_e32 v102, v102, v2
	v_sub_f32_e32 v101, v101, v2
	v_sub_f32_e32 v100, v100, v2
	v_sub_f32_e32 v99, v99, v2
	v_sub_f32_e32 v98, v98, v2
	v_sub_f32_e32 v97, v97, v2
	v_sub_f32_e32 v96, v96, v2
	v_sub_f32_e32 v95, v95, v2
	v_sub_f32_e32 v94, v94, v2
	v_sub_f32_e32 v93, v93, v2
	v_sub_f32_e32 v92, v92, v2
	v_sub_f32_e32 v91, v91, v2
	v_sub_f32_e32 v90, v90, v2
	v_sub_f32_e32 v89, v89, v2
	v_sub_f32_e32 v88, v88, v2
	v_sub_f32_e32 v87, v87, v2
	v_sub_f32_e32 v86, v86, v2
	v_sub_f32_e32 v85, v85, v2
	v_sub_f32_e32 v84, v84, v2
	v_sub_f32_e32 v83, v83, v2
	v_sub_f32_e32 v82, v82, v2
	v_sub_f32_e32 v81, v81, v2
	v_sub_f32_e32 v80, v80, v2
	v_mul_f32_e32 v171, v171, v0
